# 128 of the layer-1 mixer-A units stay at the end of M1 as tail filler, 384 move behind M2
# baseline (speedup 1.0000x reference)
; #define LAS __attribute__((address_space(3)))
;     template <class T> __device__ __forceinline__ T* w(size_t off) const { return (T*)(pp->ws + off); }
; __device__ __forceinline__ float wave_sum(float v) { v = row16_sum(v); return (rlf(v, 0) + rlf(v, 16)) + (rlf(v, 32) + rlf(v, 48)); }
; template <class T> __device__ __forceinline__ LAS T* opq(LAS T* p) { asm volatile("" : "+v"(p)); return p; }
; __device__ __forceinline__ void mixA_unit(const Ctx& c, int l, int a) {
;     const int b = a >> 7, chunk = (a >> 3) & 15, hh = a & 7, r0 = b * 2048 + chunk * 128;
;     LAS unsigned char* WmB = opq(c.lds);
;     LAS unsigned char* vT = opq(c.lds + 36864);
;     LAS float* mixed = opq((LAS float*)(c.lds + 73728));
;     LAS float* st_mean = opq((LAS float*)(c.lds + 73728 + 67584));
;     LAS float* st_rstd = st_mean + 128;
;     const bf16* VA = c.w<bf16>(WS_VA) + (size_t)r0 * 1024; const bf16* UA = c.w<bf16>(WS_UA) + (size_t)r0 * 1024; const bf16* ZA = c.w<bf16>(WS_ZA) + (size_t)r0 * 1024;
;     const int lane = c.lane, wave = c.wave, m = lane & 15, quad = lane >> 4;
; #pragma unroll
;     for (int half = 0; half < 2; ++half) {
;         u32x4 raw[8][2];
; #pragma unroll
;         for (int i = 0; i < 8; ++i) { const bf16* row = VA + (size_t)(wave * 16 + half * 8 + i) * 1024; raw[i][0] = *(const u32x4*)(row + lane * 8); raw[i][1] = *(const u32x4*)(row + 512 + lane * 8); }
; #pragma unroll
;         for (int i = 0; i < 8; ++i) {
;             float x[8], y[8]; unpack8(raw[i][0], x); unpack8(raw[i][1], y);
;             float sm = 0.f, sq = 0.f;
; #pragma unroll
;             for (int e = 0; e < 8; ++e) { sm += x[e] + y[e]; sq += x[e] * x[e] + y[e] * y[e]; }
;             sm = wave_sum(sm); sq = wave_sum(sq);
; __device__ __forceinline__ void phase_M1(Ctx& c, int l, int q, const XcdBarrier& bar) {
;     ...
;         const int u = next_unit(c, q);
;         if (u >= M1_TOTAL) break;
.LBB0_2562:
	s_or_b64 exec, exec, s[0:1]
	s_waitcnt lgkmcnt(0)
	s_barrier
	ds_read_b32 v0, v136
	s_mov_b64 s[0:1], -1
	s_waitcnt lgkmcnt(0)
	v_readfirstlane_b32 s18, v0
	v_readlane_b32 s44, v255, 62
	s_nop 3
	s_mul_i32 s45, s44, 0x610
	s_add_i32 s18, s18, s45
	s_mul_i32 s45, s44, 0x180
	s_addk_i32 s45, 0x60f
	s_cmp_gt_i32 s18, s45
	s_cbranch_scc1 .LBB0_2557
	s_cmp_gt_i32 s18, 15
	s_cbranch_scc0 .LBB0_2647
	s_cmpk_gt_u32 s18, 0x10f
	s_cbranch_scc0 .LBB0_2626
	s_cmpk_gt_u32 s18, 0x18f
	s_cbranch_scc0 .LBB0_2613
	s_cmpk_gt_u32 s18, 0x58f
	s_cbranch_scc0 .LBB0_2609
	s_lshl_b32 s0, s18, 4
	s_addk_i32 s0, 0x700
	s_and_b32 s10, s0, 0x1f80
	v_readlane_b32 s0, v251, 63
	v_mov_b32_e32 v60, v17
	v_lshlrev_b32_e32 v58, 3, v66
	v_mov_b32_e32 v63, s0
	v_readlane_b32 s0, v252, 0
	v_ashrrev_i32_e32 v59, 31, v58
	v_lshlrev_b64 v[68:69], 1, v[58:59]
	v_mov_b32_e32 v61, s0
	v_readlane_b32 s0, v252, 1
	v_readlane_b32 s2, v251, 40
	v_cmp_eq_u32_e32 vcc, 0, v66
	v_mov_b32_e32 v65, s0
	s_load_dwordx2 s[4:5], s[90:91], 0xc0
	s_lshl_b32 s0, s10, 11
	v_readlane_b32 s3, v251, 41
	s_waitcnt lgkmcnt(0)
	s_add_u32 s0, s4, s0
	s_addc_u32 s1, s5, 0
	s_add_u32 s6, s0, 0x24700000
	s_addc_u32 s7, s1, 0
	v_readlane_b32 s0, v250, 44
	v_readlane_b32 s1, v250, 45
	s_add_u32 s0, s6, s0
	s_addc_u32 s1, s7, s1
	v_lshl_add_u64 v[0:1], s[0:1], 0, v[68:69]
	global_load_dwordx4 v[70:73], v[0:1], off
	global_load_dwordx4 v[74:77], v[0:1], off offset:1024
	v_readlane_b32 s0, v250, 46
	v_readlane_b32 s1, v250, 47
	s_add_u32 s0, s6, s0
	s_addc_u32 s1, s7, s1
	v_lshl_add_u64 v[0:1], s[0:1], 0, v[68:69]
	v_readlane_b32 s0, v250, 48
	v_readlane_b32 s1, v250, 49
	s_add_u32 s0, s6, s0
	s_addc_u32 s1, s7, s1
	global_load_dwordx4 v[54:57], v[0:1], off
	global_load_dwordx4 v[50:53], v[0:1], off offset:1024
	v_lshl_add_u64 v[0:1], s[0:1], 0, v[68:69]
	v_readlane_b32 s0, v250, 50
	v_readlane_b32 s1, v250, 51
	s_add_u32 s0, s6, s0
	s_addc_u32 s1, s7, s1
	global_load_dwordx4 v[46:49], v[0:1], off
	global_load_dwordx4 v[42:45], v[0:1], off offset:1024
	v_lshl_add_u64 v[0:1], s[0:1], 0, v[68:69]
	v_readlane_b32 s0, v250, 52
	v_readlane_b32 s1, v250, 53
	s_add_u32 s0, s6, s0
	s_addc_u32 s1, s7, s1
	global_load_dwordx4 v[38:41], v[0:1], off
	global_load_dwordx4 v[34:37], v[0:1], off offset:1024
	v_lshl_add_u64 v[0:1], s[0:1], 0, v[68:69]
	v_readlane_b32 s0, v250, 54
	v_readlane_b32 s1, v250, 55
	s_add_u32 s0, s6, s0
	s_addc_u32 s1, s7, s1
	global_load_dwordx4 v[30:33], v[0:1], off
	global_load_dwordx4 v[26:29], v[0:1], off offset:1024
	v_lshl_add_u64 v[0:1], s[0:1], 0, v[68:69]
	v_readlane_b32 s0, v250, 56
	v_readlane_b32 s1, v250, 57
	s_add_u32 s0, s6, s0
	s_addc_u32 s1, s7, s1
	global_load_dwordx4 v[22:25], v[0:1], off
	global_load_dwordx4 v[18:21], v[0:1], off offset:1024
	v_lshl_add_u64 v[0:1], s[0:1], 0, v[68:69]
	v_readlane_b32 s0, v250, 58
	v_readlane_b32 s1, v250, 59
	s_add_u32 s0, s6, s0
	s_addc_u32 s1, s7, s1
	global_load_dwordx4 v[12:15], v[0:1], off
	global_load_dwordx4 v[8:11], v[0:1], off offset:1024
	v_lshl_add_u64 v[0:1], s[0:1], 0, v[68:69]
	global_load_dwordx4 v[4:7], v[0:1], off
	s_nop 0
	global_load_dwordx4 v[0:3], v[0:1], off offset:1024
	s_waitcnt vmcnt(15)
	v_lshlrev_b32_e32 v16, 16, v70
	s_waitcnt vmcnt(14)
	v_lshlrev_b32_e32 v79, 16, v74
	v_and_b32_e32 v59, 0xffff0000, v70
	v_and_b32_e32 v74, 0xffff0000, v74
	v_add_f32_e32 v83, v16, v79
	v_mul_f32_e32 v79, v79, v79
	v_fmac_f32_e32 v79, v16, v16
	v_add_f32_e32 v16, v59, v74
	v_mul_f32_e32 v74, v74, v74
	v_lshlrev_b32_e32 v67, 16, v71
	v_lshlrev_b32_e32 v80, 16, v75
	v_add_f32_e32 v83, 0, v83
	v_fmac_f32_e32 v74, v59, v59
	v_add_f32_e32 v16, v16, v83
	v_add_f32_e32 v59, v79, v74
	v_add_f32_e32 v74, v67, v80
	v_and_b32_e32 v70, 0xffff0000, v71
	v_and_b32_e32 v75, 0xffff0000, v75
	v_add_f32_e32 v16, v74, v16
	v_mul_f32_e32 v74, v80, v80
	v_fmac_f32_e32 v74, v67, v67
	v_add_f32_e32 v67, v70, v75
	v_add_f32_e32 v16, v67, v16
	v_mul_f32_e32 v67, v75, v75
	v_lshlrev_b32_e32 v71, 16, v72
	v_lshlrev_b32_e32 v81, 16, v76
	v_add_f32_e32 v59, v74, v59
	v_fmac_f32_e32 v67, v70, v70
	v_add_f32_e32 v59, v67, v59
	v_add_f32_e32 v67, v71, v81
	v_add_f32_e32 v16, v67, v16
	v_mul_f32_e32 v67, v81, v81
	v_and_b32_e32 v72, 0xffff0000, v72
	v_and_b32_e32 v76, 0xffff0000, v76
	v_fmac_f32_e32 v67, v71, v71
	v_add_f32_e32 v59, v67, v59
	v_add_f32_e32 v67, v72, v76
	v_add_f32_e32 v16, v67, v16
	v_mul_f32_e32 v67, v76, v76
	v_lshlrev_b32_e32 v78, 16, v73
	v_lshlrev_b32_e32 v82, 16, v77
	v_fmac_f32_e32 v67, v72, v72
	v_add_f32_e32 v59, v67, v59
	v_add_f32_e32 v67, v78, v82
	v_add_f32_e32 v16, v67, v16
	v_mul_f32_e32 v67, v82, v82
	v_and_b32_e32 v73, 0xffff0000, v73
	v_and_b32_e32 v77, 0xffff0000, v77
	v_fmac_f32_e32 v67, v78, v78
	v_add_f32_e32 v59, v67, v59
	v_add_f32_e32 v67, v73, v77
	v_add_f32_e32 v16, v67, v16
	v_mul_f32_e32 v67, v77, v77
	v_fmac_f32_e32 v67, v73, v73
	v_add_f32_dpp v16, v16, v16 quad_perm:[1,0,3,2] row_mask:0xf bank_mask:0xf bound_ctrl:1
	v_add_f32_e32 v59, v67, v59
	s_nop 0
	v_add_f32_dpp v16, v16, v16 quad_perm:[2,3,0,1] row_mask:0xf bank_mask:0xf bound_ctrl:1
	s_nop 1
	v_add_f32_dpp v16, v16, v16 row_half_mirror row_mask:0xf bank_mask:0xf bound_ctrl:1
	s_nop 1
	v_add_f32_dpp v16, v16, v16 row_mirror row_mask:0xf bank_mask:0xf bound_ctrl:1
	s_nop 0
	v_readlane_b32 s9, v16, 0
	v_readlane_b32 s12, v16, 16
	v_readlane_b32 s1, v16, 32
	v_readlane_b32 s11, v16, 48
	v_add_f32_dpp v16, v59, v59 quad_perm:[1,0,3,2] row_mask:0xf bank_mask:0xf bound_ctrl:1
	s_nop 1
	v_add_f32_dpp v16, v16, v16 quad_perm:[2,3,0,1] row_mask:0xf bank_mask:0xf bound_ctrl:1
	s_nop 1
	v_add_f32_dpp v16, v16, v16 row_half_mirror row_mask:0xf bank_mask:0xf bound_ctrl:1
	s_nop 1
	v_add_f32_dpp v16, v16, v16 row_mirror row_mask:0xf bank_mask:0xf bound_ctrl:1
	s_nop 0
	v_readlane_b32 s8, v16, 0
	v_readlane_b32 s14, v16, 16
	v_readlane_b32 s0, v16, 32
	v_readlane_b32 s13, v16, 48
	v_lshl_add_u32 v16, s2, 2, v65
	s_and_saveexec_b64 s[2:3], vcc
	s_cbranch_execz .LBB0_2569
	v_mov_b32_e32 v70, s14
	v_mov_b32_e32 v71, s12
	v_mov_b32_e32 v72, s13
	v_mov_b32_e32 v73, s11
	v_pk_add_f32 v[70:71], s[8:9], v[70:71]
	v_pk_add_f32 v[72:73], s[0:1], v[72:73]
	s_mov_b32 s0, 0x3a800000
	v_pk_add_f32 v[70:71], v[70:71], v[72:73]
	s_nop 0
	v_pk_mul_f32 v[70:71], v[70:71], s[0:1] op_sel_hi:[1,0]
	s_nop 0
	v_fma_f32 v59, -v71, v71, v70
	v_max_f32_e32 v59, 0, v59
	v_add_f32_e32 v59, 0x358637bd, v59
	v_mul_f32_e32 v67, 0x4b800000, v59
	v_cmp_gt_f32_e64 s[0:1], s40, v59
	s_nop 1
	v_cndmask_b32_e64 v59, v59, v67, s[0:1]
	v_rsq_f32_e32 v59, v59
	s_nop 0
	v_mul_f32_e32 v67, 0x45800000, v59
	v_cndmask_b32_e64 v59, v59, v67, s[0:1]
	ds_write2st64_b32 v16, v71, v59 offset1:2
